# MLA online softmax as well: row reference enters the QK MFMAs as C operand, per-tile subtractions only when the reference moves
# speedup vs baseline: 1.0207x; 1.0031x over previous
; #define LAS __attribute__((address_space(3)))
; template <int MODE>
; __device__ __forceinline__ void attn_unit(LAS char* lds, const AttnPtrs& A, int b, int qb) {
;     ...
;     const int tid = opaque_tid(), lane = tid & 63, r32 = lane & 31, hi = lane >> 5, wid = __builtin_amdgcn_readfirstlane(tid >> 6);
;     const int strm = (MODE == 2) ? (wid & 1) : 0;
;     const size_t rowbase = (size_t)b * SEQ; const int q0 = (MODE == 2) ? qb * 128 + (wid >> 1) * 32 : qb * 256 + wid * 32; const int cw = q0 >> 6, NT = (MODE == 2) ? 2 * qb + 2 : 4 * qb + 4;
;     const size_t qrow = rowbase + q0 + r32;
;     const bf16_t* ksrc[2]; const bf16_t* vsrc[2];
; #pragma unroll
;     for (int i = 0; i < 2; ++i) { const unsigned row = 4u * (2 * wid + i) + (lane >> 4), ch = (lane & 15) ^ (((row & 3) << 2) | ((row >> 2) & 3));
;         ksrc[i] = A.K + (rowbase + row) * A.ldk + ch * 8; vsrc[i] = A.V + (rowbase + row) * A.ldv + ch * 8; }
;     const bf16_t* k64src = nullptr;
;     if constexpr (MODE == 0) { const unsigned row = 8u * wid + (lane >> 3), ch = (lane & 7) ^ ((row >> 1) & 7); k64src = A.K64 + (rowbase + row) * 64 + ch * 8; }
;     const unsigned fK = ((r32 & 3) << 2) | ((r32 >> 2) & 3);
;     const unsigned g64 = (r32 >> 1) & 7;
;     const int q4 = (lane & 15) >> 2, p4 = lane & 3, blk = (lane >> 4) & 1;
;     unsigned vrow[2], vlow[2];
; #pragma unroll
;     for (int t = 0; t < 2; ++t) { vrow[t] = 4 * hi + 8 * t + q4; vlow[t] = (unsigned)((2 * blk + (p4 >> 1)) ^ ((hi + 2 * t) & 3)); }
;     ...
;     STAGE(0, 0); STAGE(1, 1);
;     bf16x8 qf[NQ];
; #pragma unroll
;     for (int s = 0; s < NQ; ++s) qf[s] = *(const bf16x8*)(A.Q + qrow * A.ldq + 64 * strm + 16 * s + 8 * hi);
;     if constexpr (MODE == 0) {
; #pragma unroll
;         for (int s = 0; s < 4; ++s) {
;             const u32x4 w = __builtin_bit_cast(u32x4, qf[8 + s]);
;             const f32x4 t0 = *(const f32x4*)(A.subg + (qrow * 56 + 8 * s + 4 * hi) * 2), t1 = *(const f32x4*)(A.subg + (qrow * 56 + 8 * s + 4 * hi) * 2 + 4);
;     ...
;                 if (w < 24) { const int b = w / 6, h = w % 6;
;                     att::AttnPtrs A{QMLA + h * 192, NUQ, KMLA + h * 128, 768, KROPE, VMLA + h * 128, 768, GATE + h * 128, GATE + h * 128, nullptr, 0.f, 0.f, (const float*)TAB};
;     ...
;                     att::attn_unit<0>((LAS char*)lds, A, b, qb);
.LBB0_1186:
	s_and_b64 vcc, exec, s[0:1]
	s_cbranch_vccz .LBB0_1201
	s_bfe_i32 s0, s14, 0x80000
	s_mul_i32 s0, s0, 43
	s_bfe_u32 s1, s0, 0x1000f
	s_bfe_u32 s0, s0, 0x80008
	s_add_i32 s12, s0, s1
	s_mul_i32 s0, s12, 6
	s_sub_i32 s0, s14, s0
	s_sext_i32_i8 s13, s0
	s_mul_i32 s0, s13, 0xc0
	s_ashr_i32 s1, s0, 31
	s_lshl_b64 s[0:1], s[0:1], 1
	s_add_u32 s16, s29, s0
	s_addc_u32 s17, s34, s1
	s_lshl_b32 s0, s13, 7
	s_ashr_i32 s1, s0, 31
	s_lshl_b64 s[0:1], s[0:1], 1
	s_add_u32 s52, s35, s0
	s_addc_u32 s53, s44, s1
	s_add_u32 s54, s45, s0
	s_getreg_b32 s13, hwreg(HW_REG_HW_ID, 0, 6)
	s_addc_u32 s55, s46, s1
	s_lshl_b32 s13, s13, 2
	s_and_b32 s13, s13, 0xfc
	s_add_i32 s13, s13, 0x20040
	v_mov_b32_e32 v0, s13
	ds_read_b32 v0, v0
	s_lshl_b32 s51, s49, 8
	v_mov_b64_e32 v[6:7], s[52:53]
	v_mov_b32_e32 v3, v1
	s_mov_b32 s33, 2
	s_waitcnt lgkmcnt(0)
	v_readfirstlane_b32 s13, v0
	v_mov_b32_e32 v0, v1
	s_mov_b32 s50, 0
	v_mbcnt_lo_u32_b32 v0, -1, v0
	v_mbcnt_hi_u32_b32 v8, -1, v0
	v_lshl_or_b32 v11, s13, 6, v8
	v_bfe_u32 v10, v8, 4, 2
	v_readfirstlane_b32 s13, v11
	s_ashr_i32 s13, s13, 6
	s_bfe_i64 s[14:15], s[12:13], 0x80000
	s_lshl_b32 s56, s13, 5
	s_lshl_b32 s58, s13, 3
	s_lshl_b64 s[18:19], s[14:15], 12
	s_add_i32 s56, s56, s51
	s_lshl_b32 s51, s49, 2
	v_or_b32_e32 v0, s58, v10
	s_lshl_b32 s49, s13, 1
	v_and_b32_e32 v16, 15, v8
	v_lshlrev_b32_e32 v17, 2, v10
	s_and_b32 s49, s49, 2
	v_lshl_add_u64 v[4:5], s[18:19], 0, v[0:1]
	v_bitop3_b32 v2, s49, v16, v17 bitop3:0x36
	v_mad_u64_u32 v[12:13], s[52:53], v4, s20, v[6:7]
	v_mad_i32_i24 v13, v5, s20, v13
	v_lshlrev_b32_e32 v2, 4, v2
	v_lshl_add_u64 v[38:39], v[12:13], 0, v[2:3]
	v_mov_b64_e32 v[12:13], s[54:55]
	v_mad_u64_u32 v[14:15], s[52:53], v4, s20, v[12:13]
	s_or_b32 s49, s58, 4
	v_mad_i32_i24 v15, v5, s20, v15
	v_or_b32_e32 v4, s49, v10
	v_mov_b32_e32 v5, v1
	v_lshl_add_u64 v[40:41], v[14:15], 0, v[2:3]
	s_bfe_u32 s49, s49, 0x20002
	v_lshl_add_u64 v[14:15], s[18:19], 0, v[4:5]
	v_bitop3_b32 v10, s49, v16, v17 bitop3:0x36
	v_mad_u64_u32 v[6:7], s[52:53], v14, s20, v[6:7]
	v_mad_i32_i24 v7, v15, s20, v7
	v_lshlrev_b32_e32 v4, 4, v10
	s_ashr_i32 s57, s56, 31
	v_lshl_add_u64 v[42:43], v[6:7], 0, v[4:5]
	v_mad_u64_u32 v[6:7], s[52:53], v14, s20, v[12:13]
	s_ashr_i32 s49, s56, 6
	v_and_b32_e32 v9, 31, v8
	s_add_u32 s52, s18, s56
	v_mad_i32_i24 v7, v15, s20, v7
	v_or_b32_e32 v178, s52, v9
	v_mov_b64_e32 v[14:15], s[16:17]
	s_movk_i32 s16, 0x900
	v_mad_u64_u32 v[14:15], s[16:17], v178, s16, v[14:15]
	v_mad_u64_u32 v[18:19], s[16:17], v178, 56, 0
	v_lshl_add_u64 v[50:51], v[6:7], 0, v[4:5]
	v_bfe_u32 v12, v8, 5, 1
	s_addc_u32 s53, s19, s57
	v_mov_b32_e32 v7, 0x900
	v_mov_b32_e32 v20, v19
	v_lshlrev_b32_e32 v176, 2, v12
	v_mad_i32_i24 v15, s53, v7, v15
	v_lshlrev_b32_e32 v16, 4, v12
	v_mov_b32_e32 v17, v1
	v_mad_u64_u32 v[20:21], s[16:17], s53, 56, v[20:21]
	v_lshl_add_u64 v[52:53], v[14:15], 0, v[16:17]
	v_or_b32_e32 v18, v18, v176
	v_mov_b32_e32 v19, v20
	global_load_dwordx4 v[14:17], v[52:53], off offset:256
	v_lshl_add_u64 v[58:59], v[18:19], 3, s[10:11]
	global_load_dwordx4 v[18:21], v[58:59], off offset:16
	global_load_dwordx4 v[22:25], v[58:59], off
	v_bfe_u32 v6, v8, 3, 3
	v_or_b32_e32 v6, s58, v6
	v_lshrrev_b32_e32 v10, 1, v6
	v_mov_b32_e32 v7, v1
	s_lshl_b32 s16, s13, 11
	v_xor_b32_e32 v13, v10, v8
	v_lshl_add_u64 v[26:27], s[18:19], 0, v[6:7]
	v_lshrrev_b32_e32 v28, 3, v8
	s_add_i32 s16, s16, 0
	v_lshlrev_b64 v[26:27], 7, v[26:27]
	v_and_b32_e32 v28, 2, v28
	v_bfe_u32 v29, v11, 1, 1
	v_or_b32_e32 v67, 2, v12
	v_lshlrev_b32_e32 v13, 4, v13
	s_mov_b32 m0, s16
	v_lshlrev_b32_e32 v30, 2, v8
	v_or_b32_e32 v64, v29, v28
	v_bitop3_b32 v66, v29, v12, v28 bitop3:0x36
	v_bitop3_b32 v68, v29, v67, v28 bitop3:0x36
	v_lshl_add_u64 v[26:27], s[8:9], 0, v[26:27]
	v_and_b32_e32 v28, 0x70, v13
	v_mov_b32_e32 v29, v1
	global_load_lds_dwordx4 v[38:39], off
	v_lshl_add_u64 v[54:55], v[26:27], 0, v[28:29]
	v_and_b32_e32 v13, 12, v30
	global_load_dwordx4 v[26:29], v[52:53], off offset:288
	global_load_dwordx4 v[30:33], v[58:59], off offset:80
	global_load_dwordx4 v[34:37], v[58:59], off offset:64
	s_add_i32 m0, s16, 0x400
	s_lshl_b32 s13, s13, 10
	global_load_lds_dwordx4 v[42:43], off
	s_add_i32 m0, s16, 0x4000
	s_sub_i32 s17, s16, s13
	global_load_lds_dwordx4 v[40:41], off
	s_add_i32 m0, s16, 0x4400
	v_lshl_add_u64 v[38:39], v[38:39], 0, s[94:95]
	global_load_lds_dwordx4 v[50:51], off
	s_add_i32 m0, s17, 0x8000
	v_lshl_add_u64 v[56:57], v[40:41], 0, s[94:95]
	global_load_lds_dwordx4 v[54:55], off
	s_add_i32 m0, s16, 0xa000
	v_lshl_add_u64 v[50:51], v[50:51], 0, s[94:95]
	global_load_lds_dwordx4 v[38:39], off
	v_lshl_add_u64 v[38:39], v[42:43], 0, s[94:95]
	s_add_i32 m0, s16, 0xa400
	v_bfe_u32 v62, v8, 2, 2
	global_load_lds_dwordx4 v[38:39], off
	global_load_dwordx4 v[38:41], v[52:53], off offset:320
	s_nop 0
	global_load_dwordx4 v[42:45], v[58:59], off offset:144
	global_load_dwordx4 v[46:49], v[58:59], off offset:128
	s_add_i32 m0, s16, 0xe000
	v_lshlrev_b32_e32 v177, 7, v9
	global_load_lds_dwordx4 v[56:57], off
	s_add_i32 m0, s16, 0xe400
	v_lshlrev_b32_e32 v186, 8, v9
	global_load_lds_dwordx4 v[50:51], off
	v_lshl_add_u64 v[50:51], v[54:55], 0, s[38:39]
	s_add_i32 m0, s17, 0x12000
	v_lshlrev_b32_e32 v9, 3, v8
	global_load_lds_dwordx4 v[50:51], off
	global_load_dwordx4 v[112:115], v[52:53], off
	global_load_dwordx4 v[116:119], v[52:53], off offset:32
	global_load_dwordx4 v[120:123], v[52:53], off offset:64
	global_load_dwordx4 v[124:127], v[52:53], off offset:96
	global_load_dwordx4 v[128:131], v[52:53], off offset:128
	global_load_dwordx4 v[132:135], v[52:53], off offset:160
	global_load_dwordx4 v[136:139], v[52:53], off offset:192
	global_load_dwordx4 v[140:143], v[52:53], off offset:224
	s_nop 0
	global_load_dwordx4 v[50:53], v[52:53], off offset:352
	v_or_b32_e32 v69, v13, v62
	v_lshrrev_b32_e32 v63, 1, v11
	v_bfe_u32 v11, v11, 1, 3
	s_add_i32 s17, s51, 4
	s_add_i32 s18, s13, 0
	s_lshl_b64 s[14:15], s[14:15], 19
	s_add_u32 s14, s14, 0x1b914000
	s_addc_u32 s15, s15, 0
	v_lshlrev_b64 v[6:7], 7, v[6:7]
	v_lshl_add_u64 v[180:181], s[14:15], 0, v[6:7]
	s_waitcnt vmcnt(0)
; __device__ __forceinline__ unsigned cvtpk(float lo, float hi) { unsigned r; asm("v_cvt_pk_bf16_f32 %0, %1, %2" : "=v"(r) : "v"(lo), "v"(hi)); return r; }
; __device__ __forceinline__ float bf_lo(unsigned w) { return __uint_as_float(w << 16); }
; __device__ __forceinline__ float bf_hi(unsigned w) { return __uint_as_float(w & 0xffff0000u); }
; template <int MODE>
; __device__ __forceinline__ void attn_unit(LAS char* lds, const AttnPtrs& A, int b, int qb) {
;     ...
;     const unsigned fK = ((r32 & 3) << 2) | ((r32 >> 2) & 3);
;     const unsigned g64 = (r32 >> 1) & 7;
;     const int q4 = (lane & 15) >> 2, p4 = lane & 3, blk = (lane >> 4) & 1;
;     unsigned vrow[2], vlow[2];
; #pragma unroll
;     for (int t = 0; t < 2; ++t) { vrow[t] = 4 * hi + 8 * t + q4; vlow[t] = (unsigned)((2 * blk + (p4 >> 1)) ^ ((hi + 2 * t) & 3)); }
;     ...
;     if constexpr (MODE == 0) {
; #pragma unroll
;         for (int s = 0; s < 4; ++s) {
;             const u32x4 w = __builtin_bit_cast(u32x4, qf[8 + s]);
;             const f32x4 t0 = *(const f32x4*)(A.subg + (qrow * 56 + 8 * s + 4 * hi) * 2), t1 = *(const f32x4*)(A.subg + (qrow * 56 + 8 * s + 4 * hi) * 2 + 4);
;             u32x4 o;
;             { const float a = bf_lo(w.x), b = bf_hi(w.x); o.x = cvtpk(a * t0[0] - b * t0[1], b * t0[0] + a * t0[1]); }
;             { const float a = bf_lo(w.y), b = bf_hi(w.y); o.y = cvtpk(a * t0[2] - b * t0[3], b * t0[2] + a * t0[3]); }
;             { const float a = bf_lo(w.z), b = bf_hi(w.z); o.z = cvtpk(a * t1[0] - b * t1[1], b * t1[0] + a * t1[1]); }
;             { const float a = bf_lo(w.w), b = bf_hi(w.w); o.w = cvtpk(a * t1[2] - b * t1[3], b * t1[2] + a * t1[3]); }
;             qf[8 + s] = __builtin_bit_cast(bf16x8, o);
;         }
;     }
	v_lshlrev_b32_e32 v54, 16, v14
	v_and_b32_e32 v55, 0xffff0000, v14
	v_pk_mul_f32 v[56:57], v[22:23], v[54:55]
	v_pk_mul_f32 v[22:23], v[22:23], v[54:55] op_sel:[0,1] op_sel_hi:[1,0]
	v_sub_f32_e32 v14, v56, v57
	global_load_dwordx4 v[54:57], v[58:59], off offset:208
	s_nop 0
	global_load_dwordx4 v[58:61], v[58:59], off offset:192
	v_add_f32_e32 v22, v22, v23
	v_cvt_pk_bf16_f32 v144, v14, v22
	v_lshlrev_b32_e32 v14, 16, v15
	v_and_b32_e32 v15, 0xffff0000, v15
	v_pk_mul_f32 v[22:23], v[24:25], v[14:15]
	v_pk_mul_f32 v[14:15], v[24:25], v[14:15] op_sel:[0,1] op_sel_hi:[1,0]
	v_sub_f32_e32 v22, v22, v23
	v_add_f32_e32 v14, v14, v15
	v_cvt_pk_bf16_f32 v145, v22, v14
	v_lshlrev_b32_e32 v14, 16, v16
	v_and_b32_e32 v15, 0xffff0000, v16
	v_pk_mul_f32 v[22:23], v[18:19], v[14:15]
	v_pk_mul_f32 v[14:15], v[18:19], v[14:15] op_sel:[0,1] op_sel_hi:[1,0]
	v_sub_f32_e32 v16, v22, v23
	v_add_f32_e32 v14, v14, v15
	v_cvt_pk_bf16_f32 v146, v16, v14
	v_lshlrev_b32_e32 v14, 16, v17
	v_and_b32_e32 v15, 0xffff0000, v17
	v_pk_mul_f32 v[16:17], v[20:21], v[14:15]
	v_pk_mul_f32 v[14:15], v[20:21], v[14:15] op_sel:[0,1] op_sel_hi:[1,0]
	v_sub_f32_e32 v16, v16, v17
	v_add_f32_e32 v14, v14, v15
	v_cvt_pk_bf16_f32 v147, v16, v14
	v_lshlrev_b32_e32 v14, 16, v26
	v_and_b32_e32 v15, 0xffff0000, v26
	v_pk_mul_f32 v[16:17], v[34:35], v[14:15]
	v_pk_mul_f32 v[14:15], v[34:35], v[14:15] op_sel:[0,1] op_sel_hi:[1,0]
	v_sub_f32_e32 v16, v16, v17
	v_add_f32_e32 v14, v14, v15
	v_cvt_pk_bf16_f32 v148, v16, v14
	v_lshlrev_b32_e32 v14, 16, v27
	v_and_b32_e32 v15, 0xffff0000, v27
	v_pk_mul_f32 v[16:17], v[36:37], v[14:15]
	v_pk_mul_f32 v[14:15], v[36:37], v[14:15] op_sel:[0,1] op_sel_hi:[1,0]
	v_sub_f32_e32 v16, v16, v17
	v_add_f32_e32 v14, v14, v15
	v_cvt_pk_bf16_f32 v149, v16, v14
	v_lshlrev_b32_e32 v14, 16, v28
	v_and_b32_e32 v15, 0xffff0000, v28
	v_pk_mul_f32 v[16:17], v[30:31], v[14:15]
	v_pk_mul_f32 v[14:15], v[30:31], v[14:15] op_sel:[0,1] op_sel_hi:[1,0]
	v_sub_f32_e32 v16, v16, v17
	v_add_f32_e32 v14, v14, v15
	v_cvt_pk_bf16_f32 v150, v16, v14
	v_lshlrev_b32_e32 v14, 16, v29
	v_and_b32_e32 v15, 0xffff0000, v29
	v_pk_mul_f32 v[16:17], v[32:33], v[14:15]
	v_pk_mul_f32 v[14:15], v[32:33], v[14:15] op_sel:[0,1] op_sel_hi:[1,0]
	v_sub_f32_e32 v16, v16, v17
	v_add_f32_e32 v14, v14, v15
	v_cvt_pk_bf16_f32 v151, v16, v14
	v_lshlrev_b32_e32 v14, 16, v38
	v_and_b32_e32 v15, 0xffff0000, v38
	v_pk_mul_f32 v[16:17], v[46:47], v[14:15]
	v_pk_mul_f32 v[14:15], v[46:47], v[14:15] op_sel:[0,1] op_sel_hi:[1,0]
	v_sub_f32_e32 v16, v16, v17
	v_add_f32_e32 v14, v14, v15
	v_cvt_pk_bf16_f32 v152, v16, v14
	v_lshlrev_b32_e32 v14, 16, v39
	v_and_b32_e32 v15, 0xffff0000, v39
	v_pk_mul_f32 v[16:17], v[48:49], v[14:15]
	v_pk_mul_f32 v[14:15], v[48:49], v[14:15] op_sel:[0,1] op_sel_hi:[1,0]
	v_sub_f32_e32 v16, v16, v17
	v_add_f32_e32 v14, v14, v15
	v_cvt_pk_bf16_f32 v153, v16, v14
	v_lshlrev_b32_e32 v14, 16, v40
	v_and_b32_e32 v15, 0xffff0000, v40
	v_pk_mul_f32 v[16:17], v[42:43], v[14:15]
	v_pk_mul_f32 v[14:15], v[42:43], v[14:15] op_sel:[0,1] op_sel_hi:[1,0]
	v_sub_f32_e32 v16, v16, v17
	v_add_f32_e32 v14, v14, v15
	v_cvt_pk_bf16_f32 v154, v16, v14
	v_lshlrev_b32_e32 v14, 16, v41
	v_and_b32_e32 v15, 0xffff0000, v41
	v_pk_mul_f32 v[16:17], v[44:45], v[14:15]
	v_pk_mul_f32 v[14:15], v[44:45], v[14:15] op_sel:[0,1] op_sel_hi:[1,0]
	v_sub_f32_e32 v16, v16, v17
	v_add_f32_e32 v14, v14, v15
	v_cvt_pk_bf16_f32 v155, v16, v14
	v_lshlrev_b32_e32 v14, 16, v50
	v_and_b32_e32 v15, 0xffff0000, v50
	s_waitcnt vmcnt(0)
	v_pk_mul_f32 v[16:17], v[58:59], v[14:15]
	v_pk_mul_f32 v[14:15], v[58:59], v[14:15] op_sel:[0,1] op_sel_hi:[1,0]
	v_sub_f32_e32 v16, v16, v17
	v_add_f32_e32 v14, v14, v15
	v_cvt_pk_bf16_f32 v156, v16, v14
	v_lshlrev_b32_e32 v14, 16, v51
	v_and_b32_e32 v15, 0xffff0000, v51
	v_pk_mul_f32 v[16:17], v[60:61], v[14:15]
	v_pk_mul_f32 v[14:15], v[60:61], v[14:15] op_sel:[0,1] op_sel_hi:[1,0]
	v_sub_f32_e32 v16, v16, v17
	v_add_f32_e32 v14, v14, v15
	v_cvt_pk_bf16_f32 v157, v16, v14
	v_lshlrev_b32_e32 v14, 16, v52
	v_and_b32_e32 v15, 0xffff0000, v52
	v_pk_mul_f32 v[16:17], v[54:55], v[14:15]
	v_pk_mul_f32 v[14:15], v[54:55], v[14:15] op_sel:[0,1] op_sel_hi:[1,0]
	v_sub_f32_e32 v16, v16, v17
	v_add_f32_e32 v14, v14, v15
	v_cvt_pk_bf16_f32 v158, v16, v14
	v_lshlrev_b32_e32 v14, 16, v53
	v_and_b32_e32 v15, 0xffff0000, v53
	v_pk_mul_f32 v[16:17], v[56:57], v[14:15]
	v_pk_mul_f32 v[14:15], v[56:57], v[14:15] op_sel:[0,1] op_sel_hi:[1,0]
	v_sub_f32_e32 v16, v16, v17
	v_add_f32_e32 v14, v14, v15
	v_cvt_pk_bf16_f32 v159, v16, v14
	v_mov_b32_e32 v14, 0x4000
	v_and_or_b32 v187, v9, 8, v14
	v_bitop3_b32 v9, v13, v12, v62 bitop3:0x36
	v_lshlrev_b32_e32 v188, 4, v9
	v_bitop3_b32 v9, v12, v69, 2 bitop3:0x36
	v_lshlrev_b32_e32 v189, 4, v9
	v_bitop3_b32 v9, v12, v69, 4 bitop3:0x36
	v_lshlrev_b32_e32 v190, 4, v9
	v_bitop3_b32 v9, v12, v69, 6 bitop3:0x36
	v_lshlrev_b32_e32 v191, 4, v9
	v_bitop3_b32 v9, v12, v69, 8 bitop3:0x36
	v_lshlrev_b32_e32 v192, 4, v9
	v_bitop3_b32 v9, v12, v69, 10 bitop3:0x36
	v_lshlrev_b32_e32 v193, 4, v9
	v_bitop3_b32 v9, v12, v69, 12 bitop3:0x36
	v_lshlrev_b32_e32 v194, 4, v9
	v_bitop3_b32 v9, v12, v69, 14 bitop3:0x36
	v_lshlrev_b32_e32 v195, 4, v9
	v_bitop3_b32 v9, v63, v12, 7 bitop3:0x6c
	v_lshlrev_b32_e32 v196, 4, v9
	v_bitop3_b32 v9, v12, v11, 2 bitop3:0x36
	v_lshlrev_b32_e32 v197, 4, v9
	v_bitop3_b32 v9, v12, v11, 4 bitop3:0x36
	v_lshlrev_b32_e32 v198, 4, v9
	v_bitop3_b32 v9, v12, v11, 6 bitop3:0x36
	v_lshlrev_b32_e32 v199, 4, v9
	v_and_b32_e32 v9, 12, v8
	v_or_b32_e32 v11, v66, v9
	v_or_b32_e32 v9, v68, v9
	v_lshlrev_b32_e32 v221, 4, v9
	v_bitop3_b32 v9, v8, 4, 12 bitop3:0x6c
	v_lshlrev_b32_e32 v219, 4, v11
	v_bitop3_b32 v11, v64, v9, v12 bitop3:0xde
	v_bitop3_b32 v9, v64, v9, v67 bitop3:0xde
	v_bitop3_b32 v6, v10, 7, v8 bitop3:0x48
	v_lshlrev_b32_e32 v229, 4, v9
	v_bitop3_b32 v9, v8, 8, 12 bitop3:0x6c
	v_lshl_or_b32 v180, v6, 4, v180
	v_or_b32_e32 v6, 4, v0
	v_lshlrev_b32_e32 v228, 4, v11
	v_bitop3_b32 v11, v64, v9, v12 bitop3:0xde
	v_bitop3_b32 v9, v64, v9, v67 bitop3:0xde
	v_mad_u64_u32 v[6:7], s[14:15], v6, s20, 0
	v_lshlrev_b32_e32 v231, 4, v9
	v_bitop3_b32 v9, v8, 12, v8 bitop3:0xc
	s_sext_i32_i8 s14, s12
	v_mov_b32_e32 v8, 0x600000
	v_mad_i64_i32 v[6:7], s[12:13], s14, v8, v[6:7]
	v_lshl_add_u64 v[4:5], v[6:7], 0, v[4:5]
	v_lshl_add_u64 v[182:183], v[4:5], 0, s[0:1]
	v_mad_u64_u32 v[4:5], s[12:13], v0, s20, 0
	v_mad_i64_i32 v[4:5], s[12:13], s14, v8, v[4:5]
	v_or_b32_e32 v65, v176, v62
	s_waitcnt vmcnt(0) lgkmcnt(0)
	s_barrier
; template <int MODE>
; __device__ __forceinline__ void attn_unit(LAS char* lds, const AttnPtrs& A, int b, int qb) {
;     ...
;     f32x16 o1[4];
; #pragma unroll
;     for (int c = 0; c < 4; ++c) o1[c] = f32x16{};
;     float m1 = -1e30f, l1 = 0.f;
;     unsigned long long mw_next = 0ull;
;     if constexpr (MODE == 1) { mw_next = A.MASK[qrow * 64]; asm volatile("" : "+v"(mw_next)); }
;     bf16x8 pk[4]; float a1 = 1.f;
;     ...
;     int st_cur = 0, st_nn = 2;
	v_lshlrev_b32_e32 v230, 4, v11
	v_bitop3_b32 v11, v64, v9, v12 bitop3:0xde
	v_bitop3_b32 v9, v64, v9, v67 bitop3:0xde
	v_lshl_add_u64 v[2:3], v[4:5], 0, v[2:3]
	v_mov_b32_e32 v14, v1
	v_mov_b32_e32 v15, v1
	v_lshlrev_b32_e32 v218, 8, v65
	v_lshlrev_b32_e32 v232, 4, v11
	v_lshlrev_b32_e32 v233, 4, v9
	v_lshl_add_u64 v[184:185], v[2:3], 0, s[0:1]
	v_mov_b32_e32 v0, v1
	v_mov_b32_e32 v2, v1
	v_mov_b32_e32 v3, v1
	v_mov_b32_e32 v4, v1
	v_mov_b32_e32 v5, v1
	v_mov_b32_e32 v6, v1
	v_mov_b32_e32 v7, v1
	v_mov_b32_e32 v8, v1
	v_mov_b32_e32 v9, v1
	v_mov_b32_e32 v10, v1
	v_mov_b32_e32 v11, v1
	v_mov_b32_e32 v12, v1
	v_mov_b32_e32 v13, v1
	v_mov_b64_e32 v[30:31], v[14:15]
	v_mov_b64_e32 v[46:47], v[14:15]
	v_mov_b64_e32 v[62:63], v[14:15]
	v_mov_b64_e32 v[78:79], v[14:15]
	v_mov_b32_e32 v179, s53
	v_or_b32_e32 v220, 0x800, v218
	v_or_b32_e32 v222, 0x1000, v218
	v_or_b32_e32 v223, 0x1800, v218
	v_or_b32_e32 v224, 0x2000, v218
	v_or_b32_e32 v225, 0x2800, v218
	v_or_b32_e32 v226, 0x3000, v218
	v_or_b32_e32 v227, 0x3800, v218
	v_mov_b32_e32 v235, 0xf149f2ca
	v_mov_b32_e32 v252, 0
	v_mov_b64_e32 v[236:237], 0
	v_mov_b64_e32 v[238:239], 0
	v_mov_b64_e32 v[240:241], 0
	v_mov_b64_e32 v[242:243], 0
	v_mov_b64_e32 v[244:245], 0
	v_mov_b64_e32 v[246:247], 0
	v_mov_b64_e32 v[248:249], 0
	v_mov_b64_e32 v[250:251], 0
	v_mov_b32_e32 v234, 0
	v_mov_b64_e32 v[28:29], v[12:13]
	v_mov_b64_e32 v[26:27], v[10:11]
	v_mov_b64_e32 v[24:25], v[8:9]
	v_mov_b64_e32 v[22:23], v[6:7]
	v_mov_b64_e32 v[20:21], v[4:5]
	v_mov_b64_e32 v[18:19], v[2:3]
	v_mov_b64_e32 v[16:17], v[0:1]
	v_mov_b64_e32 v[44:45], v[12:13]
	v_mov_b64_e32 v[42:43], v[10:11]
	v_mov_b64_e32 v[40:41], v[8:9]
	v_mov_b64_e32 v[38:39], v[6:7]
	v_mov_b64_e32 v[36:37], v[4:5]
	v_mov_b64_e32 v[34:35], v[2:3]
	v_mov_b64_e32 v[32:33], v[0:1]
	v_mov_b64_e32 v[60:61], v[12:13]
	v_mov_b64_e32 v[58:59], v[10:11]
	v_mov_b64_e32 v[56:57], v[8:9]
	v_mov_b64_e32 v[54:55], v[6:7]
	v_mov_b64_e32 v[52:53], v[4:5]
	v_mov_b64_e32 v[50:51], v[2:3]
	v_mov_b64_e32 v[48:49], v[0:1]
	v_mov_b64_e32 v[76:77], v[12:13]
	v_mov_b64_e32 v[74:75], v[10:11]
	v_mov_b64_e32 v[72:73], v[8:9]
	v_mov_b64_e32 v[70:71], v[6:7]
	v_mov_b64_e32 v[68:69], v[4:5]
	v_mov_b64_e32 v[66:67], v[2:3]
	v_mov_b64_e32 v[64:65], v[0:1]
	s_mov_b32 s14, 0

; __device__ __forceinline__ float max_x32(float v) { const unsigned u = __float_as_uint(v); auto r = __builtin_amdgcn_permlane32_swap(u, u, false, false); return fmaxf(__uint_as_float(r[0]), __uint_as_float(r[1])); }
; template <bool MASKED>
; __device__ __forceinline__ void softmax_tile(f32x16& s0, f32x16& s1, float& m, float& l, float& alpha, unsigned mlo, unsigned mhi, bf16x8 (&pk)[4]) {
;     ...
;     float mx = fmaxf(s0[0], s1[0]);
; #pragma unroll
;     for (int r = 1; r < 16; ++r) mx = fmaxf(mx, fmaxf(s0[r], s1[r]));
;     mx = max_x32(mx);
;     const float mn = fmaxf(m, mx);
;     alpha = __builtin_amdgcn_exp2f(m - mn); m = mn;
.LBB0_1190:
	s_cmp_gt_i32 s14, s49
	s_cbranch_scc1 .LBB0_1194
	s_mul_i32 s15, s50, 0xa000
	s_add_i32 s15, s15, 0
	v_add_u32_e32 v0, s15, v186
	v_add_u32_e32 v6, v0, v188
	v_add_u32_e32 v14, v0, v189
	ds_read_b128 v[2:5], v6
	ds_read_b128 v[6:9], v6 offset:8192
	ds_read_b128 v[10:13], v14
	ds_read_b128 v[160:163], v14 offset:8192
	v_add_u32_e32 v14, v0, v190
	ds_read_b128 v[164:167], v14
	ds_read_b128 v[168:171], v14 offset:8192
	v_add_u32_e32 v14, v0, v191
	ds_read_b128 v[172:175], v14 offset:8192
	ds_read_b128 v[206:209], v14
	v_add_u32_e32 v14, s15, v177
	s_waitcnt lgkmcnt(0)
	v_mfma_f32_32x32x16_bf16 v[96:111], v[2:5], v[112:115], v[236:251]
	v_mfma_f32_32x32x16_bf16 v[80:95], v[6:9], v[112:115], v[236:251]
	v_mfma_f32_32x32x16_bf16 v[96:111], v[10:13], v[116:119], v[96:111]
	v_mfma_f32_32x32x16_bf16 v[80:95], v[160:163], v[116:119], v[80:95]
	v_mfma_f32_32x32x16_bf16 v[96:111], v[164:167], v[120:123], v[96:111]
	v_mfma_f32_32x32x16_bf16 v[80:95], v[168:171], v[120:123], v[80:95]
	v_mfma_f32_32x32x16_bf16 v[96:111], v[206:209], v[124:127], v[96:111]
	v_mfma_f32_32x32x16_bf16 v[80:95], v[172:175], v[124:127], v[80:95]
	v_add_u32_e32 v6, v0, v192
	v_add_u32_e32 v15, v0, v193
	ds_read_b128 v[2:5], v6
	ds_read_b128 v[6:9], v6 offset:8192
	ds_read_b128 v[10:13], v15
	ds_read_b128 v[160:163], v15 offset:8192
	v_add_u32_e32 v15, v0, v194
	v_add_u32_e32 v0, v0, v195
	ds_read_b128 v[164:167], v15
	ds_read_b128 v[168:171], v15 offset:8192
	ds_read_b128 v[172:175], v0 offset:8192
	ds_read_b128 v[206:209], v0
	s_waitcnt lgkmcnt(0)
	v_mfma_f32_32x32x16_bf16 v[96:111], v[2:5], v[128:131], v[96:111]
	v_mfma_f32_32x32x16_bf16 v[80:95], v[6:9], v[128:131], v[80:95]
	v_mfma_f32_32x32x16_bf16 v[96:111], v[10:13], v[132:135], v[96:111]
	v_mfma_f32_32x32x16_bf16 v[80:95], v[160:163], v[132:135], v[80:95]
	v_mfma_f32_32x32x16_bf16 v[96:111], v[164:167], v[136:139], v[96:111]
	v_mfma_f32_32x32x16_bf16 v[80:95], v[168:171], v[136:139], v[80:95]
	v_mfma_f32_32x32x16_bf16 v[96:111], v[206:209], v[140:143], v[96:111]
	v_mfma_f32_32x32x16_bf16 v[80:95], v[172:175], v[140:143], v[80:95]
	v_add_u32_e32 v0, v14, v196
	ds_read_b128 v[2:5], v0 offset:32768
	ds_read_b128 v[6:9], v0 offset:36864
	v_add_u32_e32 v0, v14, v197
	ds_read_b128 v[10:13], v0 offset:32768
	ds_read_b128 v[160:163], v0 offset:36864
	v_add_u32_e32 v0, v14, v198
	ds_read_b128 v[164:167], v0 offset:32768
	ds_read_b128 v[168:171], v0 offset:36864
	v_add_u32_e32 v0, v14, v199
	ds_read_b128 v[172:175], v0 offset:36864
	ds_read_b128 v[206:209], v0 offset:32768
	s_waitcnt lgkmcnt(0)
	v_mfma_f32_32x32x16_bf16 v[96:111], v[2:5], v[144:147], v[96:111]
	v_mfma_f32_32x32x16_bf16 v[80:95], v[6:9], v[144:147], v[80:95]
	v_mfma_f32_32x32x16_bf16 v[96:111], v[10:13], v[148:151], v[96:111]
	v_mfma_f32_32x32x16_bf16 v[80:95], v[160:163], v[148:151], v[80:95]
	v_mfma_f32_32x32x16_bf16 v[96:111], v[164:167], v[152:155], v[96:111]
	v_mfma_f32_32x32x16_bf16 v[80:95], v[168:171], v[152:155], v[80:95]
	v_mfma_f32_32x32x16_bf16 v[96:111], v[206:209], v[156:159], v[96:111]
	v_mfma_f32_32x32x16_bf16 v[80:95], v[172:175], v[156:159], v[80:95]
	s_nop 11
	v_max3_f32 v160, v96, v97, v98
	v_max3_f32 v161, v99, v100, v101
	v_max3_f32 v162, v102, v103, v104
	v_max3_f32 v163, v105, v106, v107
	v_max3_f32 v164, v108, v109, v110
	v_max3_f32 v165, v111, v80, v81
	v_max3_f32 v166, v82, v83, v84
	v_max3_f32 v167, v85, v86, v87
	v_max3_f32 v168, v88, v89, v90
	v_max3_f32 v169, v91, v92, v93
	v_max3_f32 v160, v160, v161, v162
	v_max3_f32 v163, v163, v164, v165
	v_max3_f32 v166, v166, v167, v168
	v_max3_f32 v169, v169, v94, v95
	v_max3_f32 v160, v160, v163, v166
	v_max_f32_e32 v160, v160, v169
	v_mov_b32_e32 v161, v160
	s_nop 1
	v_permlane32_swap_b32_e32 v160, v161
	v_max_f32_e32 v14, v160, v161
	v_add_f32_e32 v14, v14, v252
	v_max_f32_e32 v14, v235, v14
	v_sub_f32_e32 v160, v14, v235
	v_cmp_lt_f32_e32 vcc, 8.0, v160
	s_nop 1
	v_cndmask_b32_e32 v14, v235, v14, vcc
	v_sub_f32_e32 v0, v235, v14
	v_sub_f32_e32 v160, v14, v252
	v_cmp_neq_f32_e32 vcc, 0, v160
	s_cbranch_vccz .Lm0_cfast
	v_sub_f32_e32 v96, v96, v160
	v_sub_f32_e32 v97, v97, v160
	v_sub_f32_e32 v98, v98, v160
	v_sub_f32_e32 v99, v99, v160
	v_sub_f32_e32 v100, v100, v160
	v_sub_f32_e32 v101, v101, v160
	v_sub_f32_e32 v102, v102, v160
	v_sub_f32_e32 v103, v103, v160
	v_sub_f32_e32 v104, v104, v160
	v_sub_f32_e32 v105, v105, v160
	v_sub_f32_e32 v106, v106, v160
	v_sub_f32_e32 v107, v107, v160
	v_sub_f32_e32 v108, v108, v160
	v_sub_f32_e32 v109, v109, v160
	v_sub_f32_e32 v110, v110, v160
	v_sub_f32_e32 v111, v111, v160
	v_sub_f32_e32 v80, v80, v160
	v_sub_f32_e32 v81, v81, v160
	v_sub_f32_e32 v82, v82, v160
	v_sub_f32_e32 v83, v83, v160
	v_sub_f32_e32 v84, v84, v160
	v_sub_f32_e32 v85, v85, v160
	v_sub_f32_e32 v86, v86, v160
	v_sub_f32_e32 v87, v87, v160
	v_sub_f32_e32 v88, v88, v160
	v_sub_f32_e32 v89, v89, v160
	v_sub_f32_e32 v90, v90, v160
	v_sub_f32_e32 v91, v91, v160
	v_sub_f32_e32 v92, v92, v160
	v_sub_f32_e32 v93, v93, v160
	v_sub_f32_e32 v94, v94, v160
	v_sub_f32_e32 v95, v95, v160
	v_mov_b32_e32 v252, v14
	v_sub_f32_e32 v236, 0, v14
	v_sub_f32_e32 v237, 0, v14
	v_sub_f32_e32 v238, 0, v14
	v_sub_f32_e32 v239, 0, v14
	v_sub_f32_e32 v240, 0, v14
	v_sub_f32_e32 v241, 0, v14
	v_sub_f32_e32 v242, 0, v14
	v_sub_f32_e32 v243, 0, v14
	v_sub_f32_e32 v244, 0, v14
	v_sub_f32_e32 v245, 0, v14
	v_sub_f32_e32 v246, 0, v14
	v_sub_f32_e32 v247, 0, v14
	v_sub_f32_e32 v248, 0, v14
	v_sub_f32_e32 v249, 0, v14
	v_sub_f32_e32 v250, 0, v14
	v_sub_f32_e32 v251, 0, v14
; __device__ __forceinline__ unsigned cvtpk(float lo, float hi) { unsigned r; asm("v_cvt_pk_bf16_f32 %0, %1, %2" : "=v"(r) : "v"(lo), "v"(hi)); return r; }
; template <bool MASKED>
; __device__ __forceinline__ void softmax_tile(f32x16& s0, f32x16& s1, float& m, float& l, float& alpha, unsigned mlo, unsigned mhi, bf16x8 (&pk)[4]) {
;     ...
;     alpha = __builtin_amdgcn_exp2f(m - mn); m = mn;
;     float sum = 0.f;
; #pragma unroll
;     for (int r = 0; r < 16; ++r) {
;         float p0 = __builtin_amdgcn_exp2f(s0[r] - mn), p1 = __builtin_amdgcn_exp2f(s1[r] - mn);
;         if (MASKED) { if (s0[r] <= -1e29f) p0 = 0.f; if (s1[r] <= -1e29f) p1 = 0.f; }
;         s0[r] = p0; s1[r] = p1; sum += p0 + p1;
;     }
;     l = l * alpha + sum;
; #pragma unroll
;     for (int k2 = 0; k2 < 2; ++k2) {
;         u32x4 a, b;
;         a.x = cvtpk(s0[8 * k2 + 0], s0[8 * k2 + 1]); a.y = cvtpk(s0[8 * k2 + 2], s0[8 * k2 + 3]); a.z = cvtpk(s0[8 * k2 + 4], s0[8 * k2 + 5]); a.w = cvtpk(s0[8 * k2 + 6], s0[8 * k2 + 7]);
;         b.x = cvtpk(s1[8 * k2 + 0], s1[8 * k2 + 1]); b.y = cvtpk(s1[8 * k2 + 2], s1[8 * k2 + 3]); b.z = cvtpk(s1[8 * k2 + 4], s1[8 * k2 + 5]); b.w = cvtpk(s1[8 * k2 + 6], s1[8 * k2 + 7]);
;         pk[k2] = __builtin_bit_cast(bf16x8, a); pk[2 + k2] = __builtin_bit_cast(bf16x8, b);
;     }
.Lm0_cfast:
	v_exp_f32_e32 v0, v0
	v_exp_f32_e32 v96, v96
	v_exp_f32_e32 v97, v97
	v_exp_f32_e32 v98, v98
	v_exp_f32_e32 v99, v99
	v_exp_f32_e32 v100, v100
	v_exp_f32_e32 v101, v101
	v_exp_f32_e32 v102, v102
	v_exp_f32_e32 v103, v103
	v_exp_f32_e32 v104, v104
	v_exp_f32_e32 v105, v105
	v_exp_f32_e32 v106, v106
	v_exp_f32_e32 v107, v107
	v_exp_f32_e32 v108, v108
	v_exp_f32_e32 v109, v109
	v_exp_f32_e32 v110, v110
	v_exp_f32_e32 v111, v111
	v_exp_f32_e32 v80, v80
	v_exp_f32_e32 v81, v81
	v_exp_f32_e32 v82, v82
	v_exp_f32_e32 v83, v83
	v_exp_f32_e32 v84, v84
	v_exp_f32_e32 v85, v85
	v_exp_f32_e32 v86, v86
	v_exp_f32_e32 v87, v87
	v_exp_f32_e32 v88, v88
	v_exp_f32_e32 v89, v89
	v_exp_f32_e32 v90, v90
	v_exp_f32_e32 v91, v91
	v_exp_f32_e32 v92, v92
	v_exp_f32_e32 v93, v93
	v_exp_f32_e32 v94, v94
	v_exp_f32_e32 v95, v95
	v_pk_add_f32 v[160:161], v[96:97], v[98:99]
	v_pk_add_f32 v[162:163], v[100:101], v[102:103]
	v_pk_add_f32 v[164:165], v[104:105], v[106:107]
	v_pk_add_f32 v[166:167], v[108:109], v[110:111]
	v_pk_add_f32 v[168:169], v[80:81], v[82:83]
	v_pk_add_f32 v[170:171], v[84:85], v[86:87]
	v_pk_add_f32 v[172:173], v[88:89], v[90:91]
	v_pk_add_f32 v[174:175], v[92:93], v[94:95]
	v_pk_add_f32 v[160:161], v[160:161], v[162:163]
	v_pk_add_f32 v[164:165], v[164:165], v[166:167]
	v_pk_add_f32 v[168:169], v[168:169], v[170:171]
	v_pk_add_f32 v[172:173], v[172:173], v[174:175]
	v_pk_add_f32 v[160:161], v[160:161], v[164:165]
	v_pk_add_f32 v[168:169], v[168:169], v[172:173]
	v_pk_add_f32 v[160:161], v[160:161], v[168:169]
	v_add_f32_e32 v15, v160, v161
	v_cvt_pk_bf16_f32 v2, v80, v81
	v_cvt_pk_bf16_f32 v3, v82, v83
	v_cvt_pk_bf16_f32 v4, v84, v85
	v_cvt_pk_bf16_f32 v5, v86, v87
	v_cvt_pk_bf16_f32 v6, v88, v89
	v_cvt_pk_bf16_f32 v7, v90, v91
	v_cvt_pk_bf16_f32 v8, v92, v93
	v_cvt_pk_bf16_f32 v9, v94, v95
	v_cvt_pk_bf16_f32 v80, v104, v105
	v_cvt_pk_bf16_f32 v81, v106, v107
	v_cvt_pk_bf16_f32 v82, v108, v109
	v_cvt_pk_bf16_f32 v83, v110, v111
	v_cvt_pk_bf16_f32 v10, v96, v97
	v_cvt_pk_bf16_f32 v11, v98, v99
	v_cvt_pk_bf16_f32 v12, v100, v101
	v_cvt_pk_bf16_f32 v13, v102, v103
	v_fmac_f32_e32 v15, v234, v0
	v_cmp_neq_f32_e32 vcc, 1.0, v0
	s_cbranch_vccz .LBB0_1193
	v_pk_mul_f32 v[78:79], v[78:79], v[0:1] op_sel_hi:[1,0]
	v_pk_mul_f32 v[76:77], v[76:77], v[0:1] op_sel_hi:[1,0]
	v_pk_mul_f32 v[74:75], v[74:75], v[0:1] op_sel_hi:[1,0]
	v_pk_mul_f32 v[72:73], v[72:73], v[0:1] op_sel_hi:[1,0]
	v_pk_mul_f32 v[70:71], v[70:71], v[0:1] op_sel_hi:[1,0]
	v_pk_mul_f32 v[68:69], v[68:69], v[0:1] op_sel_hi:[1,0]
	v_pk_mul_f32 v[66:67], v[66:67], v[0:1] op_sel_hi:[1,0]
	v_pk_mul_f32 v[64:65], v[64:65], v[0:1] op_sel_hi:[1,0]
	v_pk_mul_f32 v[62:63], v[62:63], v[0:1] op_sel_hi:[1,0]
	v_pk_mul_f32 v[60:61], v[60:61], v[0:1] op_sel_hi:[1,0]
	v_pk_mul_f32 v[58:59], v[58:59], v[0:1] op_sel_hi:[1,0]
	v_pk_mul_f32 v[56:57], v[56:57], v[0:1] op_sel_hi:[1,0]
	v_pk_mul_f32 v[54:55], v[54:55], v[0:1] op_sel_hi:[1,0]
	v_pk_mul_f32 v[52:53], v[52:53], v[0:1] op_sel_hi:[1,0]
	v_pk_mul_f32 v[50:51], v[50:51], v[0:1] op_sel_hi:[1,0]
	v_pk_mul_f32 v[48:49], v[48:49], v[0:1] op_sel_hi:[1,0]
	v_pk_mul_f32 v[46:47], v[46:47], v[0:1] op_sel_hi:[1,0]
	v_pk_mul_f32 v[44:45], v[44:45], v[0:1] op_sel_hi:[1,0]
	v_pk_mul_f32 v[42:43], v[42:43], v[0:1] op_sel_hi:[1,0]
	v_pk_mul_f32 v[40:41], v[40:41], v[0:1] op_sel_hi:[1,0]
	v_pk_mul_f32 v[38:39], v[38:39], v[0:1] op_sel_hi:[1,0]
	v_pk_mul_f32 v[36:37], v[36:37], v[0:1] op_sel_hi:[1,0]
	v_pk_mul_f32 v[34:35], v[34:35], v[0:1] op_sel_hi:[1,0]
	v_pk_mul_f32 v[32:33], v[32:33], v[0:1] op_sel_hi:[1,0]
	v_pk_mul_f32 v[30:31], v[30:31], v[0:1] op_sel_hi:[1,0]
	v_pk_mul_f32 v[28:29], v[28:29], v[0:1] op_sel_hi:[1,0]
	v_pk_mul_f32 v[26:27], v[26:27], v[0:1] op_sel_hi:[1,0]
	v_pk_mul_f32 v[24:25], v[24:25], v[0:1] op_sel_hi:[1,0]
	v_pk_mul_f32 v[22:23], v[22:23], v[0:1] op_sel_hi:[1,0]
	v_pk_mul_f32 v[20:21], v[20:21], v[0:1] op_sel_hi:[1,0]
	v_pk_mul_f32 v[18:19], v[18:19], v[0:1] op_sel_hi:[1,0]
	v_pk_mul_f32 v[16:17], v[16:17], v[0:1] op_sel_hi:[1,0]
